# attention main loop: LDS reads prefetched into free VGPRs (counted lgkmcnt), 2-chain max, hoisted bpermute addr
# speedup vs baseline: 1.0081x; 1.0081x over previous
; DI void attn_unit(LAS unsigned char* lds, int tid, const bf16* __restrict__ P, const bf16* __restrict__ Vt, bf16* MG, int b, int h, int qrow0, int jt0, int jt1,
;                   float lam, float oscale, const float* subg) {
;     ...
;     const int lane = tid & 63, wave = tid >> 6, r32 = lane & 31, hi = lane >> 5;
;     const int qb = wave >> 1, m = wave & 1;
;     const int qrow = qrow0 + qb * 32 + r32;
;     bf16x8 qf[4];
; #pragma unroll
;     for (int ks = 0; ks < 4; ++ks) qf[ks] = *(const bf16x8*)(P + (size_t)qrow * NIN + h * 128 + m * 64 + ks * 16 + hi * 8);
;     f32x16 O[4];
; #pragma unroll
;     for (int es = 0; es < 4; ++es)
; #pragma unroll
;         for (int i = 0; i < 16; ++i) O[es][i] = 0.f;
;     float mrun = 0.f, lrun = 0.f;
;     u32x4 kreg[2], vreg[2];
;     const bf16* vbase = Vt + (size_t)(b * 4 + h) * 128 * NKEY;
.LBB0_299:
	s_or_b64 exec, exec, s[2:3]
	s_lshl_b32 s17, s15, 7
	s_lshl_b32 s36, s17, 1
	s_mov_b64 s[40:41], s[36:37]
	v_writelane_b32 v253, s40, 6
	s_movk_i32 s15, 0x2200
	v_mad_i64_i32 v[102:103], s[2:3], v99, s15, 0
	v_writelane_b32 v253, s41, 7
	v_writelane_b32 v253, s42, 8
	v_mad_i64_i32 v[100:101], s[2:3], v100, s15, 0
	v_writelane_b32 v253, s43, 9
	s_bfe_u32 s2, s14, 0x10002
	v_writelane_b32 v253, s44, 10
	s_lshl_b32 s3, s2, 8
	v_writelane_b32 v253, s45, 11
	s_add_i32 s15, s9, s3
	s_lshl_b32 s3, s2, 12
	s_lshl_b32 s2, s2, 2
	v_writelane_b32 v253, s46, 12
	s_add_i32 s16, s12, s3
	s_add_i32 s2, s8, s2
	s_and_b32 s3, s13, 3
	v_writelane_b32 v253, s47, 13
	s_add_i32 s3, s2, s3
	v_writelane_b32 v253, s48, 14
	v_writelane_b32 v253, s49, 15
	s_add_u32 s18, s74, s36
	v_and_b32_e32 v177, 63, v98
	v_add_u32_e32 v178, v97, v176
	v_writelane_b32 v253, s50, 16
	s_addc_u32 s19, s75, 0
	v_mov_b32_e32 v97, v147
	v_and_b32_e32 v98, 7, v98
	v_writelane_b32 v253, s51, 17
	v_lshl_add_u64 v[160:161], s[18:19], 0, v[96:97]
	v_mad_i64_i32 v[96:97], s[18:19], s3, v217, v[102:103]
	v_lshlrev_b32_e32 v146, 4, v98
	v_writelane_b32 v253, s52, 18
	v_lshl_add_u64 v[96:97], v[96:97], 0, v[146:147]
	v_writelane_b32 v253, s53, 19
	v_lshl_add_u64 v[162:163], s[6:7], 0, v[96:97]
	v_mad_i64_i32 v[96:97], s[18:19], s3, v217, v[100:101]
	v_writelane_b32 v253, s54, 20
	v_lshl_add_u64 v[96:97], v[96:97], 0, v[146:147]
	v_ashrrev_i32_e32 v157, 31, v156
	v_add_f32_e32 v158, 0, v158
	s_mov_b32 s2, 1
	v_writelane_b32 v253, s55, 21
	v_lshl_add_u64 v[164:165], s[6:7], 0, v[96:97]
	s_mov_b32 s17, 0
	s_mov_b32 s21, 0
	s_mov_b32 s18, 1
	v_and_b32_e32 v209, 64, v210
	v_add_u32_e32 v209, 64, v209
	v_xor_b32_e32 v250, 32, v210
	v_cmp_lt_i32_e64 s[24:25], v250, v209
	s_nop 1
	v_cndmask_b32_e64 v209, v210, v250, s[24:25]
	v_lshlrev_b32_e32 v209, 2, v209
.LBB0_300:
	s_mov_b32 s19, s2
	s_mulk_i32 s2, 0x4400
	s_add_i32 s3, s2, 0
	s_lshl_b32 s20, s19, 10
	s_add_i32 s20, s3, s20
	v_add_u32_e32 v96, s3, v171
	s_waitcnt vmcnt(2)
	ds_write_b128 v96, v[132:135]
	v_add_u32_e32 v96, s20, v172
	s_waitcnt vmcnt(1)
	ds_write_b128 v96, v[128:131] offset:52224
	v_add_u32_e32 v96, s3, v173
	ds_write_b128 v96, v[136:139]
	v_add_u32_e32 v96, s20, v174
	s_waitcnt vmcnt(0)
	ds_write_b128 v96, v[140:143] offset:52224
	v_add_u32_e32 v146, s2, v175
	s_cmp_lg_u64 s[4:5], 0
	s_cbranch_scc1 .Latt1_preA
	s_mul_i32 s22, s21, 0x4800
	s_add_i32 s22, s22, 0xcc00
	v_add_u32_e32 v250, s22, v178
	ds_read_b128 v[188:191], v250
	ds_read_b128 v[192:195], v250 offset:32
	ds_read_b128 v[196:199], v250 offset:64
	ds_read_b128 v[200:203], v250 offset:96
	ds_read_b128 v[204:207], v250 offset:4608
	ds_read_b128 v[218:221], v250 offset:4640
	ds_read_b128 v[222:225], v250 offset:4672
	ds_read_b128 v[226:229], v250 offset:4704
	ds_read_b128 v[230:233], v250 offset:9216
	ds_read_b128 v[234:237], v250 offset:9248
	ds_read_b128 v[238:241], v250 offset:9280
	s_waitcnt lgkmcnt(11)
	s_branch .Latt1_bar

.Latt1_bar:
	s_barrier
	s_cmpk_lg_i32 s17, 0x1080
	s_cbranch_scc0 .Latt1_noload
	s_cmp_lt_u32 s18, 63
	s_cselect_b32 s3, s16, s15
	s_add_i32 s3, s3, s17
	v_add_u32_e32 v96, s3, v155
	v_mad_i64_i32 v[96:97], s[22:23], v96, s72, v[160:161]
	v_add_u32_e32 v98, s3, v170
	global_load_dwordx4 v[128:131], v[162:163], off
	v_mad_i64_i32 v[98:99], s[22:23], v98, s72, v[160:161]
	global_load_dwordx4 v[132:135], v[96:97], off offset:1024
	global_load_dwordx4 v[136:139], v[98:99], off offset:1024
	global_load_dwordx4 v[140:143], v[164:165], off
.Latt1_noload:
	s_cmp_lg_u64 s[4:5], 0
	s_cbranch_scc0 .Latt1_B
	ds_read_b128 v[180:183], v146
	ds_read_b128 v[184:187], v146 offset:8704
	ds_read_b128 v[188:191], v146 offset:32
	ds_read_b128 v[192:195], v146 offset:8736
	ds_read_b128 v[196:199], v146 offset:64
	ds_read_b128 v[200:203], v146 offset:8768
	ds_read_b128 v[204:207], v146 offset:96
	ds_read_b128 v[218:221], v146 offset:8800
	s_mul_i32 s22, s19, 0x4800
	s_add_i32 s22, s22, 0xcc00
	v_add_u32_e32 v250, s22, v178
	ds_read_b128 v[222:225], v250
	ds_read_b128 v[226:229], v250 offset:32
	ds_read_b128 v[230:233], v250 offset:64
	ds_read_b128 v[234:237], v250 offset:96
	ds_read_b128 v[238:241], v250 offset:4608
	ds_read_b128 v[242:245], v250 offset:4640
	ds_read_b128 v[246:249], v250 offset:4672
	s_waitcnt lgkmcnt(14)
	v_mfma_f32_32x32x16_bf16 v[80:95], v[180:183], v[112:115], v[64:79]
	s_waitcnt lgkmcnt(13)
	v_mfma_f32_32x32x16_bf16 v[96:111], v[184:187], v[112:115], v[64:79]
	s_waitcnt lgkmcnt(12)
	v_mfma_f32_32x32x16_bf16 v[80:95], v[188:191], v[116:119], v[80:95]
	s_waitcnt lgkmcnt(11)
	v_mfma_f32_32x32x16_bf16 v[96:111], v[192:195], v[116:119], v[96:111]
	s_waitcnt lgkmcnt(10)
	v_mfma_f32_32x32x16_bf16 v[80:95], v[196:199], v[120:123], v[80:95]
	s_waitcnt lgkmcnt(9)
	v_mfma_f32_32x32x16_bf16 v[96:111], v[200:203], v[120:123], v[96:111]
	s_waitcnt lgkmcnt(8)
	v_mfma_f32_32x32x16_bf16 v[80:95], v[204:207], v[124:127], v[80:95]
	s_waitcnt lgkmcnt(7)
	v_mfma_f32_32x32x16_bf16 v[96:111], v[218:221], v[124:127], v[96:111]
	s_nop 13
	v_max3_f32 v145, v80, v81, v82
	v_max3_f32 v146, v96, v97, v98
	v_max3_f32 v145, v145, v83, v84
	v_max3_f32 v146, v146, v99, v100
	v_max3_f32 v145, v145, v85, v86
	v_max3_f32 v146, v146, v101, v102
	v_max3_f32 v145, v145, v87, v88
	v_max3_f32 v146, v146, v103, v104
	v_max3_f32 v145, v145, v89, v90
	v_max3_f32 v146, v146, v105, v106
	v_max3_f32 v145, v145, v91, v92
	v_max3_f32 v146, v146, v107, v108
	v_max3_f32 v145, v145, v93, v94
	v_max3_f32 v146, v146, v109, v110
	v_max3_f32 v145, v145, v95, v111
	v_max_f32_e32 v145, v145, v146
	ds_bpermute_b32 v146, v209, v145
	s_waitcnt lgkmcnt(0)
	v_max_f32_e32 v146, v145, v146
	v_cmp_lt_f32_e32 vcc, 0x41000000, v146
	s_cbranch_vccz .Latt1A_nors
	s_nop 0
	v_cndmask_b32_e32 v146, 0, v146, vcc
	v_exp_f32_e64 v150, -v146
	v_add_f32_e32 v159, v159, v146
	v_xor_b32_e32 v64, 0x80000000, v159
	v_mov_b32_e32 v65, v64
	v_mov_b32_e32 v66, v64
	v_mov_b32_e32 v67, v64
	v_mov_b32_e32 v68, v64
	v_mov_b32_e32 v69, v64
	v_mov_b32_e32 v70, v64
	v_mov_b32_e32 v71, v64
	v_mov_b32_e32 v72, v64
	v_mov_b32_e32 v73, v64
	v_mov_b32_e32 v74, v64
	v_mov_b32_e32 v75, v64
	v_mov_b32_e32 v76, v64
	v_mov_b32_e32 v77, v64
	v_mov_b32_e32 v78, v64
	v_mov_b32_e32 v79, v64
	v_mul_f32_e32 v158, v158, v150
	v_pk_mul_f32 v[14:15], v[14:15], v[150:151] op_sel_hi:[1,0]
	v_pk_mul_f32 v[12:13], v[12:13], v[150:151] op_sel_hi:[1,0]
	v_pk_mul_f32 v[10:11], v[10:11], v[150:151] op_sel_hi:[1,0]
	v_pk_mul_f32 v[8:9], v[8:9], v[150:151] op_sel_hi:[1,0]
	v_pk_mul_f32 v[6:7], v[6:7], v[150:151] op_sel_hi:[1,0]
	v_pk_mul_f32 v[4:5], v[4:5], v[150:151] op_sel_hi:[1,0]
	v_pk_mul_f32 v[2:3], v[2:3], v[150:151] op_sel_hi:[1,0]
	v_pk_mul_f32 v[0:1], v[0:1], v[150:151] op_sel_hi:[1,0]
	v_pk_mul_f32 v[30:31], v[30:31], v[150:151] op_sel_hi:[1,0]
	v_pk_mul_f32 v[28:29], v[28:29], v[150:151] op_sel_hi:[1,0]
	v_pk_mul_f32 v[26:27], v[26:27], v[150:151] op_sel_hi:[1,0]
	v_pk_mul_f32 v[24:25], v[24:25], v[150:151] op_sel_hi:[1,0]
	v_pk_mul_f32 v[22:23], v[22:23], v[150:151] op_sel_hi:[1,0]
	v_pk_mul_f32 v[20:21], v[20:21], v[150:151] op_sel_hi:[1,0]
	v_pk_mul_f32 v[18:19], v[18:19], v[150:151] op_sel_hi:[1,0]
	v_pk_mul_f32 v[16:17], v[16:17], v[150:151] op_sel_hi:[1,0]
	v_pk_mul_f32 v[46:47], v[46:47], v[150:151] op_sel_hi:[1,0]
	v_pk_mul_f32 v[44:45], v[44:45], v[150:151] op_sel_hi:[1,0]
	v_pk_mul_f32 v[42:43], v[42:43], v[150:151] op_sel_hi:[1,0]
	v_pk_mul_f32 v[40:41], v[40:41], v[150:151] op_sel_hi:[1,0]
	v_pk_mul_f32 v[38:39], v[38:39], v[150:151] op_sel_hi:[1,0]
	v_pk_mul_f32 v[36:37], v[36:37], v[150:151] op_sel_hi:[1,0]
	v_pk_mul_f32 v[34:35], v[34:35], v[150:151] op_sel_hi:[1,0]
	v_pk_mul_f32 v[32:33], v[32:33], v[150:151] op_sel_hi:[1,0]
	v_pk_mul_f32 v[62:63], v[62:63], v[150:151] op_sel_hi:[1,0]
	v_pk_mul_f32 v[60:61], v[60:61], v[150:151] op_sel_hi:[1,0]
	v_pk_mul_f32 v[58:59], v[58:59], v[150:151] op_sel_hi:[1,0]
	v_pk_mul_f32 v[56:57], v[56:57], v[150:151] op_sel_hi:[1,0]
	v_pk_mul_f32 v[54:55], v[54:55], v[150:151] op_sel_hi:[1,0]
	v_pk_mul_f32 v[52:53], v[52:53], v[150:151] op_sel_hi:[1,0]
	v_pk_mul_f32 v[50:51], v[50:51], v[150:151] op_sel_hi:[1,0]
	v_pk_mul_f32 v[48:49], v[48:49], v[150:151] op_sel_hi:[1,0]
	v_pk_add_f32 v[80:81], v[80:81], v[146:147] op_sel_hi:[1,0] neg_lo:[0,1] neg_hi:[0,1]
	v_pk_add_f32 v[96:97], v[96:97], v[146:147] op_sel_hi:[1,0] neg_lo:[0,1] neg_hi:[0,1]
	v_pk_add_f32 v[82:83], v[82:83], v[146:147] op_sel_hi:[1,0] neg_lo:[0,1] neg_hi:[0,1]
	v_pk_add_f32 v[98:99], v[98:99], v[146:147] op_sel_hi:[1,0] neg_lo:[0,1] neg_hi:[0,1]
	v_pk_add_f32 v[84:85], v[84:85], v[146:147] op_sel_hi:[1,0] neg_lo:[0,1] neg_hi:[0,1]
	v_pk_add_f32 v[100:101], v[100:101], v[146:147] op_sel_hi:[1,0] neg_lo:[0,1] neg_hi:[0,1]
	v_pk_add_f32 v[86:87], v[86:87], v[146:147] op_sel_hi:[1,0] neg_lo:[0,1] neg_hi:[0,1]
	v_pk_add_f32 v[102:103], v[102:103], v[146:147] op_sel_hi:[1,0] neg_lo:[0,1] neg_hi:[0,1]
	v_pk_add_f32 v[88:89], v[88:89], v[146:147] op_sel_hi:[1,0] neg_lo:[0,1] neg_hi:[0,1]
	v_pk_add_f32 v[104:105], v[104:105], v[146:147] op_sel_hi:[1,0] neg_lo:[0,1] neg_hi:[0,1]
	v_pk_add_f32 v[90:91], v[90:91], v[146:147] op_sel_hi:[1,0] neg_lo:[0,1] neg_hi:[0,1]
	v_pk_add_f32 v[106:107], v[106:107], v[146:147] op_sel_hi:[1,0] neg_lo:[0,1] neg_hi:[0,1]
	v_pk_add_f32 v[92:93], v[92:93], v[146:147] op_sel_hi:[1,0] neg_lo:[0,1] neg_hi:[0,1]
	v_pk_add_f32 v[108:109], v[108:109], v[146:147] op_sel_hi:[1,0] neg_lo:[0,1] neg_hi:[0,1]
	v_pk_add_f32 v[94:95], v[94:95], v[146:147] op_sel_hi:[1,0] neg_lo:[0,1] neg_hi:[0,1]
	v_pk_add_f32 v[110:111], v[110:111], v[146:147] op_sel_hi:[1,0] neg_lo:[0,1] neg_hi:[0,1]
.Latt1A_nors:
	ds_read_b128 v[188:191], v250 offset:4704
	ds_read_b128 v[192:195], v250 offset:9216
	ds_read_b128 v[196:199], v250 offset:9248
	ds_read_b128 v[200:203], v250 offset:9280
	ds_read_b128 v[204:207], v250 offset:9312
	ds_read_b128 v[218:221], v250 offset:13824
	v_exp_f32_e32 v145, v80
	v_exp_f32_e32 v179, v96
	v_exp_f32_e32 v146, v81
	v_exp_f32_e32 v150, v97
	v_exp_f32_e32 v186, v98
	v_add_f32_e32 v151, v179, v145
	v_exp_f32_e32 v180, v99
	v_pk_add_f32 v[80:81], v[150:151], v[146:147]
	v_exp_f32_e32 v151, v82
	v_pk_add_f32 v[96:97], v[80:81], v[80:81] op_sel_hi:[0,1]
	v_exp_f32_e32 v96, v83
	v_exp_f32_e32 v98, v101
	v_add_f32_e32 v181, v186, v151
	v_exp_f32_e32 v88, v88
	v_pk_add_f32 v[80:81], v[180:181], v[96:97]
	v_exp_f32_e32 v97, v84
	v_pk_add_f32 v[82:83], v[80:81], v[80:81] op_sel_hi:[0,1]
	v_exp_f32_e32 v181, v100
	v_exp_f32_e32 v82, v85
	v_exp_f32_e32 v100, v103
	v_exp_f32_e32 v182, v105
	v_add_f32_e32 v99, v181, v97
	v_pk_add_f32 v[80:81], v[98:99], v[82:83]
	v_exp_f32_e32 v83, v86
	v_pk_add_f32 v[84:85], v[80:81], v[80:81] op_sel_hi:[0,1]
	v_exp_f32_e32 v99, v102
	v_exp_f32_e32 v84, v87
	v_exp_f32_e32 v184, v107
	v_add_f32_e32 v101, v99, v83
	v_pk_add_f32 v[80:81], v[100:101], v[84:85]
	v_exp_f32_e32 v101, v104
	v_pk_add_f32 v[102:103], v[80:81], v[80:81] op_sel_hi:[0,1]
	v_exp_f32_e32 v102, v89
	v_exp_f32_e32 v89, v90
	v_add_f32_e32 v183, v101, v88
	v_cvt_pk_bf16_f32 v82, v97, v82
	v_pk_add_f32 v[80:81], v[182:183], v[102:103]
	v_exp_f32_e32 v103, v106
	v_pk_add_f32 v[104:105], v[80:81], v[80:81] op_sel_hi:[0,1]
	v_exp_f32_e32 v104, v91
	v_exp_f32_e32 v183, v108
	v_add_f32_e32 v185, v103, v89
	v_exp_f32_e32 v106, v109
	v_pk_add_f32 v[80:81], v[184:185], v[104:105]
	v_exp_f32_e32 v105, v92
	v_pk_add_f32 v[90:91], v[80:81], v[80:81] op_sel_hi:[0,1]
	v_exp_f32_e32 v90, v93
	v_exp_f32_e32 v108, v111
	v_add_f32_e32 v107, v183, v105
	v_cvt_pk_bf16_f32 v89, v89, v104
	v_pk_add_f32 v[80:81], v[106:107], v[90:91]
	v_exp_f32_e32 v91, v94
	v_pk_add_f32 v[92:93], v[80:81], v[80:81] op_sel_hi:[0,1]
	v_exp_f32_e32 v107, v110
	v_exp_f32_e32 v92, v95
	v_cvt_pk_bf16_f32 v86, v181, v98
	v_add_f32_e32 v109, v107, v91
	v_pk_add_f32 v[80:81], v[108:109], v[92:93]
	v_cvt_pk_bf16_f32 v87, v99, v100
	v_add_f32_e32 v109, v80, v81
	v_cvt_pk_bf16_f32 v81, v151, v96
	v_cvt_pk_bf16_f32 v88, v88, v102
	v_cvt_pk_bf16_f32 v91, v91, v92
	v_cvt_pk_bf16_f32 v92, v101, v182
	v_cvt_pk_bf16_f32 v93, v103, v184
	v_cvt_pk_bf16_f32 v80, v145, v146
	v_cvt_pk_bf16_f32 v83, v83, v84
	v_cvt_pk_bf16_f32 v90, v105, v90
	v_cvt_pk_bf16_f32 v84, v179, v150
	v_cvt_pk_bf16_f32 v85, v186, v180
	v_cvt_pk_bf16_f32 v94, v183, v106
	v_cvt_pk_bf16_f32 v95, v107, v108
	v_add_f32_e32 v158, v158, v109
	ds_read_b128 v[180:183], v250 offset:13856
	ds_read_b128 v[184:187], v250 offset:13888
	ds_read_b128 v[96:99], v250 offset:13920
	v_mfma_f32_32x32x16_bf16 v[48:63], v[222:225], v[80:83], v[48:63]
	v_mfma_f32_32x32x16_bf16 v[48:63], v[226:229], v[88:91], v[48:63]
	v_mfma_f32_32x32x16_bf16 v[48:63], v[230:233], v[84:87], v[48:63]
	v_mfma_f32_32x32x16_bf16 v[48:63], v[234:237], v[92:95], v[48:63]
	v_mfma_f32_32x32x16_bf16 v[32:47], v[238:241], v[80:83], v[32:47]
	v_mfma_f32_32x32x16_bf16 v[32:47], v[242:245], v[88:91], v[32:47]
	v_mfma_f32_32x32x16_bf16 v[32:47], v[246:249], v[84:87], v[32:47]
	s_waitcnt lgkmcnt(8)
	v_mfma_f32_32x32x16_bf16 v[32:47], v[188:191], v[92:95], v[32:47]
	s_waitcnt lgkmcnt(7)
	v_mfma_f32_32x32x16_bf16 v[16:31], v[192:195], v[80:83], v[16:31]
	s_waitcnt lgkmcnt(6)
	v_mfma_f32_32x32x16_bf16 v[16:31], v[196:199], v[88:91], v[16:31]
	s_waitcnt lgkmcnt(5)
	v_mfma_f32_32x32x16_bf16 v[16:31], v[200:203], v[84:87], v[16:31]
	s_waitcnt lgkmcnt(4)
	v_mfma_f32_32x32x16_bf16 v[16:31], v[204:207], v[92:95], v[16:31]
	s_waitcnt lgkmcnt(3)
	v_mfma_f32_32x32x16_bf16 v[0:15], v[218:221], v[80:83], v[0:15]
	s_waitcnt lgkmcnt(2)
	v_mfma_f32_32x32x16_bf16 v[0:15], v[180:183], v[88:91], v[0:15]
	s_waitcnt lgkmcnt(1)
	v_mfma_f32_32x32x16_bf16 v[0:15], v[184:187], v[84:87], v[0:15]
	s_waitcnt lgkmcnt(0)
	v_mfma_f32_32x32x16_bf16 v[0:15], v[96:99], v[92:95], v[0:15]
	s_branch .Latt1_end
.Latt1_B:
	ds_read_b128 v[242:245], v250 offset:9312
	ds_read_b128 v[246:249], v250 offset:13824
	ds_read_b128 v[180:183], v250 offset:13856
	ds_read_b128 v[184:187], v250 offset:13888
	s_waitcnt lgkmcnt(14)
	v_mfma_f32_32x32x16_bf16 v[48:63], v[188:191], v[80:83], v[48:63]
	ds_read_b128 v[188:191], v250 offset:13920
	s_waitcnt lgkmcnt(14)
	v_mfma_f32_32x32x16_bf16 v[48:63], v[192:195], v[88:91], v[48:63]
	ds_read_b128 v[192:195], v146
	s_waitcnt lgkmcnt(14)
	v_mfma_f32_32x32x16_bf16 v[48:63], v[196:199], v[84:87], v[48:63]
	ds_read_b128 v[196:199], v146 offset:8704
	s_waitcnt lgkmcnt(14)
	v_mfma_f32_32x32x16_bf16 v[48:63], v[200:203], v[92:95], v[48:63]
	ds_read_b128 v[200:203], v146 offset:32
	s_waitcnt lgkmcnt(14)
	v_mfma_f32_32x32x16_bf16 v[32:47], v[204:207], v[80:83], v[32:47]
	ds_read_b128 v[204:207], v146 offset:8736
	s_waitcnt lgkmcnt(14)
	v_mfma_f32_32x32x16_bf16 v[32:47], v[218:221], v[88:91], v[32:47]
	ds_read_b128 v[218:221], v146 offset:64
	s_waitcnt lgkmcnt(14)
	v_mfma_f32_32x32x16_bf16 v[32:47], v[222:225], v[84:87], v[32:47]
	ds_read_b128 v[222:225], v146 offset:8768
	s_waitcnt lgkmcnt(14)
	v_mfma_f32_32x32x16_bf16 v[32:47], v[226:229], v[92:95], v[32:47]
	ds_read_b128 v[226:229], v146 offset:96
	s_waitcnt lgkmcnt(14)
	v_mfma_f32_32x32x16_bf16 v[16:31], v[230:233], v[80:83], v[16:31]
	ds_read_b128 v[230:233], v146 offset:8800
	s_waitcnt lgkmcnt(14)
	v_mfma_f32_32x32x16_bf16 v[16:31], v[234:237], v[88:91], v[16:31]
	s_waitcnt lgkmcnt(13)
	v_mfma_f32_32x32x16_bf16 v[16:31], v[238:241], v[84:87], v[16:31]
	s_waitcnt lgkmcnt(12)
	v_mfma_f32_32x32x16_bf16 v[16:31], v[242:245], v[92:95], v[16:31]
	s_waitcnt lgkmcnt(11)
	v_mfma_f32_32x32x16_bf16 v[0:15], v[246:249], v[80:83], v[0:15]
	s_waitcnt lgkmcnt(10)
	v_mfma_f32_32x32x16_bf16 v[0:15], v[180:183], v[88:91], v[0:15]
	s_waitcnt lgkmcnt(9)
	v_mfma_f32_32x32x16_bf16 v[0:15], v[184:187], v[84:87], v[0:15]
	s_waitcnt lgkmcnt(8)
	v_mfma_f32_32x32x16_bf16 v[0:15], v[188:191], v[92:95], v[0:15]
	s_waitcnt lgkmcnt(7)
	v_mfma_f32_32x32x16_bf16 v[96:111], v[192:195], v[112:115], v[64:79]
	s_waitcnt lgkmcnt(6)
	v_mfma_f32_32x32x16_bf16 v[80:95], v[196:199], v[112:115], v[64:79]
	s_waitcnt lgkmcnt(5)
	v_mfma_f32_32x32x16_bf16 v[96:111], v[200:203], v[116:119], v[96:111]
	s_waitcnt lgkmcnt(4)
	v_mfma_f32_32x32x16_bf16 v[80:95], v[204:207], v[116:119], v[80:95]
	s_waitcnt lgkmcnt(3)
	v_mfma_f32_32x32x16_bf16 v[96:111], v[218:221], v[120:123], v[96:111]
	s_waitcnt lgkmcnt(2)
	v_mfma_f32_32x32x16_bf16 v[80:95], v[222:225], v[120:123], v[80:95]
	s_waitcnt lgkmcnt(1)
	v_mfma_f32_32x32x16_bf16 v[96:111], v[226:229], v[124:127], v[96:111]
	s_waitcnt lgkmcnt(0)
	v_mfma_f32_32x32x16_bf16 v[80:95], v[230:233], v[124:127], v[80:95]
	s_nop 13
	v_max3_f32 v145, v80, v81, v82
	v_max3_f32 v146, v96, v97, v98
	v_max3_f32 v145, v145, v83, v84
	v_max3_f32 v146, v146, v99, v100
	v_max3_f32 v145, v145, v85, v86
	v_max3_f32 v146, v146, v101, v102
	v_max3_f32 v145, v145, v87, v88
	v_max3_f32 v146, v146, v103, v104
	v_max3_f32 v145, v145, v89, v90
	v_max3_f32 v146, v146, v105, v106
	v_max3_f32 v145, v145, v91, v92
	v_max3_f32 v146, v146, v107, v108
	v_max3_f32 v145, v145, v93, v94
	v_max3_f32 v146, v146, v109, v110
	v_max3_f32 v145, v145, v95, v111
	v_max_f32_e32 v145, v145, v146
	ds_bpermute_b32 v146, v209, v145
	s_waitcnt lgkmcnt(0)
	v_max_f32_e32 v146, v145, v146
	v_cmp_lt_f32_e32 vcc, 0x41000000, v146
	s_cbranch_vccz .Latt1B_nors
	s_nop 0
	v_cndmask_b32_e32 v146, 0, v146, vcc
	v_exp_f32_e64 v150, -v146
	v_add_f32_e32 v159, v159, v146
	v_xor_b32_e32 v64, 0x80000000, v159
	v_mov_b32_e32 v65, v64
	v_mov_b32_e32 v66, v64
	v_mov_b32_e32 v67, v64
	v_mov_b32_e32 v68, v64
	v_mov_b32_e32 v69, v64
	v_mov_b32_e32 v70, v64
	v_mov_b32_e32 v71, v64
	v_mov_b32_e32 v72, v64
	v_mov_b32_e32 v73, v64
	v_mov_b32_e32 v74, v64
	v_mov_b32_e32 v75, v64
	v_mov_b32_e32 v76, v64
	v_mov_b32_e32 v77, v64
	v_mov_b32_e32 v78, v64
	v_mov_b32_e32 v79, v64
	v_mul_f32_e32 v158, v158, v150
	v_pk_mul_f32 v[14:15], v[14:15], v[150:151] op_sel_hi:[1,0]
	v_pk_mul_f32 v[12:13], v[12:13], v[150:151] op_sel_hi:[1,0]
	v_pk_mul_f32 v[10:11], v[10:11], v[150:151] op_sel_hi:[1,0]
	v_pk_mul_f32 v[8:9], v[8:9], v[150:151] op_sel_hi:[1,0]
	v_pk_mul_f32 v[6:7], v[6:7], v[150:151] op_sel_hi:[1,0]
	v_pk_mul_f32 v[4:5], v[4:5], v[150:151] op_sel_hi:[1,0]
	v_pk_mul_f32 v[2:3], v[2:3], v[150:151] op_sel_hi:[1,0]
	v_pk_mul_f32 v[0:1], v[0:1], v[150:151] op_sel_hi:[1,0]
	v_pk_mul_f32 v[30:31], v[30:31], v[150:151] op_sel_hi:[1,0]
	v_pk_mul_f32 v[28:29], v[28:29], v[150:151] op_sel_hi:[1,0]
	v_pk_mul_f32 v[26:27], v[26:27], v[150:151] op_sel_hi:[1,0]
	v_pk_mul_f32 v[24:25], v[24:25], v[150:151] op_sel_hi:[1,0]
	v_pk_mul_f32 v[22:23], v[22:23], v[150:151] op_sel_hi:[1,0]
	v_pk_mul_f32 v[20:21], v[20:21], v[150:151] op_sel_hi:[1,0]
	v_pk_mul_f32 v[18:19], v[18:19], v[150:151] op_sel_hi:[1,0]
	v_pk_mul_f32 v[16:17], v[16:17], v[150:151] op_sel_hi:[1,0]
	v_pk_mul_f32 v[46:47], v[46:47], v[150:151] op_sel_hi:[1,0]
	v_pk_mul_f32 v[44:45], v[44:45], v[150:151] op_sel_hi:[1,0]
	v_pk_mul_f32 v[42:43], v[42:43], v[150:151] op_sel_hi:[1,0]
	v_pk_mul_f32 v[40:41], v[40:41], v[150:151] op_sel_hi:[1,0]
	v_pk_mul_f32 v[38:39], v[38:39], v[150:151] op_sel_hi:[1,0]
	v_pk_mul_f32 v[36:37], v[36:37], v[150:151] op_sel_hi:[1,0]
	v_pk_mul_f32 v[34:35], v[34:35], v[150:151] op_sel_hi:[1,0]
	v_pk_mul_f32 v[32:33], v[32:33], v[150:151] op_sel_hi:[1,0]
	v_pk_mul_f32 v[62:63], v[62:63], v[150:151] op_sel_hi:[1,0]
	v_pk_mul_f32 v[60:61], v[60:61], v[150:151] op_sel_hi:[1,0]
	v_pk_mul_f32 v[58:59], v[58:59], v[150:151] op_sel_hi:[1,0]
	v_pk_mul_f32 v[56:57], v[56:57], v[150:151] op_sel_hi:[1,0]
	v_pk_mul_f32 v[54:55], v[54:55], v[150:151] op_sel_hi:[1,0]
	v_pk_mul_f32 v[52:53], v[52:53], v[150:151] op_sel_hi:[1,0]
	v_pk_mul_f32 v[50:51], v[50:51], v[150:151] op_sel_hi:[1,0]
	v_pk_mul_f32 v[48:49], v[48:49], v[150:151] op_sel_hi:[1,0]
	v_pk_add_f32 v[80:81], v[80:81], v[146:147] op_sel_hi:[1,0] neg_lo:[0,1] neg_hi:[0,1]
	v_pk_add_f32 v[96:97], v[96:97], v[146:147] op_sel_hi:[1,0] neg_lo:[0,1] neg_hi:[0,1]
	v_pk_add_f32 v[82:83], v[82:83], v[146:147] op_sel_hi:[1,0] neg_lo:[0,1] neg_hi:[0,1]
	v_pk_add_f32 v[98:99], v[98:99], v[146:147] op_sel_hi:[1,0] neg_lo:[0,1] neg_hi:[0,1]
	v_pk_add_f32 v[84:85], v[84:85], v[146:147] op_sel_hi:[1,0] neg_lo:[0,1] neg_hi:[0,1]
	v_pk_add_f32 v[100:101], v[100:101], v[146:147] op_sel_hi:[1,0] neg_lo:[0,1] neg_hi:[0,1]
	v_pk_add_f32 v[86:87], v[86:87], v[146:147] op_sel_hi:[1,0] neg_lo:[0,1] neg_hi:[0,1]
	v_pk_add_f32 v[102:103], v[102:103], v[146:147] op_sel_hi:[1,0] neg_lo:[0,1] neg_hi:[0,1]
	v_pk_add_f32 v[88:89], v[88:89], v[146:147] op_sel_hi:[1,0] neg_lo:[0,1] neg_hi:[0,1]
	v_pk_add_f32 v[104:105], v[104:105], v[146:147] op_sel_hi:[1,0] neg_lo:[0,1] neg_hi:[0,1]
	v_pk_add_f32 v[90:91], v[90:91], v[146:147] op_sel_hi:[1,0] neg_lo:[0,1] neg_hi:[0,1]
	v_pk_add_f32 v[106:107], v[106:107], v[146:147] op_sel_hi:[1,0] neg_lo:[0,1] neg_hi:[0,1]
	v_pk_add_f32 v[92:93], v[92:93], v[146:147] op_sel_hi:[1,0] neg_lo:[0,1] neg_hi:[0,1]
	v_pk_add_f32 v[108:109], v[108:109], v[146:147] op_sel_hi:[1,0] neg_lo:[0,1] neg_hi:[0,1]
	v_pk_add_f32 v[94:95], v[94:95], v[146:147] op_sel_hi:[1,0] neg_lo:[0,1] neg_hi:[0,1]
	v_pk_add_f32 v[110:111], v[110:111], v[146:147] op_sel_hi:[1,0] neg_lo:[0,1] neg_hi:[0,1]

; DI void attn_unit(LAS unsigned char* lds, int tid, const bf16* __restrict__ P, const bf16* __restrict__ Vt, bf16* MG, int b, int h, int qrow0, int jt0, int jt1,
;                   float lam, float oscale, const float* subg) {
;     ...
;         pbuf = buf; buf = (buf == 2) ? 0 : buf + 1;
;     }
.Latt1_end:
	s_add_i32 s2, s19, 1
	s_cmp_lg_u32 s19, 2
	s_cselect_b32 s2, s2, 0
	s_add_i32 s17, s17, 64
	s_mov_b64 s[22:23], 0x80
	s_add_i32 s18, s18, 1
	v_lshl_add_u64 v[162:163], v[162:163], 0, s[22:23]
	s_cmpk_eq_i32 s17, 0x10c0
	v_lshl_add_u64 v[164:165], v[164:165], 0, s[22:23]
	s_cbranch_scc1 .LBB0_312
	s_mov_b32 s21, s19
	s_branch .LBB0_300
